# attention softmax: cross-half max via v_permlane32_swap (no LDS round trip), two max chains, dependent fma/exp/add pairs spaced apart
# speedup vs baseline: 1.0057x; 1.0057x over previous
; #define MFMA32(a, b, c) __builtin_amdgcn_mfma_f32_32x32x16_bf16((a), (b), (c), 0, 0, 0)
;     ...
;   for (int kt = 0; kt < nkt; ++kt) {
;     __syncthreads();
; #pragma unroll
;     for (int i = 0; i < 3; ++i) {
;       int c = tid + 256 * i, key = c / 12, part = c % 12;
;       *(u32x4*)(Ks + key * 104 + part * 8) = rk[i];
;     }
; #pragma unroll
;     for (int i = 0; i < 2; ++i) {
;       int c = tid + 256 * i, dv = c >> 3, part = c & 7;
;       *(u32x2*)(Vs + dv * 68 + part * 8) = mk2(rv[i].x, rv[i].y);
;       *(u32x2*)(Vs + dv * 68 + part * 8 + 4) = mk2(rv[i].z, rv[i].w);
;     }
;     __syncthreads();
;     if (kt + 1 < nkt) loadt(kt + 1);
;     f32x16 S[2][2];
; #pragma unroll
;     for (int g = 0; g < 2; ++g) { zero_acc(S[g][0]); zero_acc(S[g][1]); }
; #pragma unroll
;     for (int mt = 0; mt < 2; ++mt)
; #pragma unroll
;       for (int s = 0; s < 6; ++s) {
;         const bf16x8 a = *(const bf16x8*)(Ks + (mt * 32 + l31) * 104 + s * 16 + hh * 8);
;         S[0][mt] = MFMA32(a, qf[0][s], S[0][mt]);
;         S[1][mt] = MFMA32(a, qf[1][s], S[1][mt]);
;       }
;     asm volatile("s_nop 15\n\ts_nop 15" ::: "memory");
; #pragma unroll
;     for (int g = 0; g < 2; ++g) {
;       float mx = -1e30f;
; #pragma unroll
;       for (int mt = 0; mt < 2; ++mt)
; #pragma unroll
;         for (int r = 0; r < 16; ++r) mx = fmaxf(mx, S[g][mt][r]);
;       mx = fmaxf(mx, __shfl_xor(mx, 32)) * scl;
;       const float mnew = fmaxf(mrun[g], mx);
;       const float alpha = __builtin_amdgcn_exp2f(mrun[g] - mnew);
;       mrun[g] = mnew;
;       float ps = 0.f;
; #pragma unroll
;       for (int mt = 0; mt < 2; ++mt)
; #pragma unroll
;         for (int r = 0; r < 16; ++r) { float e = __builtin_amdgcn_exp2f(fmaf(S[g][mt][r], scl, -mnew)); S[g][mt][r] = e; ps += e; }
;       lsum[g] = lsum[g] * alpha + ps;
;       if (__builtin_amdgcn_ballot_w64(alpha != 1.f) != 0ull) {
; #pragma unroll
;         for (int d = 0; d < 2; ++d)
; #pragma unroll
;           for (int r = 0; r < 16; ++r) O[g][d][r] *= alpha;
;       }
.Latt_kt:
	v_lshl_add_u64 v[220:221], s[8:9], 0, v[212:213]
	s_barrier
	s_waitcnt vmcnt(4)
	ds_write_b128 v239, v[178:181]
	s_waitcnt vmcnt(3)
	ds_write_b128 v240, v[182:185]
	s_waitcnt vmcnt(2)
	ds_write_b128 v241, v[186:189]
	s_waitcnt vmcnt(1)
	ds_write2_b64 v242, v[190:191], v[192:193] offset1:1
	s_waitcnt vmcnt(0)
	ds_write2_b64 v243, v[194:195], v[196:197] offset1:1
	s_waitcnt lgkmcnt(0)
	s_barrier
	global_load_dwordx4 v[178:181], v[220:221], off
	v_lshl_add_u64 v[220:221], s[8:9], 0, v[210:211]
	global_load_dwordx4 v[182:185], v[220:221], off
	v_lshl_add_u64 v[220:221], s[8:9], 0, v[208:209]
	global_load_dwordx4 v[186:189], v[220:221], off
	v_lshl_add_u64 v[220:221], s[8:9], 0, v[206:207]
	global_load_dwordx4 v[190:193], v[220:221], off
	v_lshl_add_u64 v[220:221], s[8:9], 0, v[204:205]
	global_load_dwordx4 v[194:197], v[220:221], off
	ds_read_b128 v[220:223], v238
	ds_read_b128 v[224:227], v238 offset:6656
	ds_read_b128 v[230:233], v238 offset:32
	s_waitcnt lgkmcnt(2)
	v_mfma_f32_32x32x16_bf16 v[66:81], v[220:223], v[170:173], 0
	ds_read_b128 v[220:223], v238 offset:6688
	s_waitcnt lgkmcnt(2)
	v_mfma_f32_32x32x16_bf16 v[82:97], v[224:227], v[170:173], 0
	ds_read_b128 v[224:227], v238 offset:64
	s_waitcnt lgkmcnt(2)
	v_mfma_f32_32x32x16_bf16 v[66:81], v[230:233], v[158:161], v[66:81]
	ds_read_b128 v[230:233], v238 offset:6720
	s_waitcnt lgkmcnt(2)
	v_mfma_f32_32x32x16_bf16 v[82:97], v[220:223], v[158:161], v[82:97]
	ds_read_b128 v[220:223], v238 offset:96
	s_waitcnt lgkmcnt(2)
	v_mfma_f32_32x32x16_bf16 v[66:81], v[224:227], v[154:157], v[66:81]
	ds_read_b128 v[224:227], v238 offset:6752
	s_waitcnt lgkmcnt(2)
	v_mfma_f32_32x32x16_bf16 v[82:97], v[230:233], v[154:157], v[82:97]
	ds_read_b128 v[230:233], v238 offset:128
	s_waitcnt lgkmcnt(2)
	v_mfma_f32_32x32x16_bf16 v[66:81], v[220:223], v[142:145], v[66:81]
	ds_read_b128 v[220:223], v238 offset:6784
	s_waitcnt lgkmcnt(2)
	v_mfma_f32_32x32x16_bf16 v[82:97], v[224:227], v[142:145], v[82:97]
	ds_read_b128 v[224:227], v238 offset:160
	s_waitcnt lgkmcnt(2)
	v_mfma_f32_32x32x16_bf16 v[66:81], v[230:233], v[138:141], v[66:81]
	ds_read_b128 v[230:233], v238 offset:6816
	s_waitcnt lgkmcnt(2)
	v_mfma_f32_32x32x16_bf16 v[82:97], v[220:223], v[138:141], v[82:97]
	s_waitcnt lgkmcnt(1)
	v_mfma_f32_32x32x16_bf16 v[66:81], v[224:227], v[130:133], v[66:81]
	s_waitcnt lgkmcnt(0)
	v_mfma_f32_32x32x16_bf16 v[82:97], v[230:233], v[130:133], v[82:97]
	ds_read_b128 v[220:223], v238
	ds_read_b128 v[224:227], v238 offset:6656
	ds_read_b128 v[230:233], v238 offset:32
	s_waitcnt lgkmcnt(2)
	v_mfma_f32_32x32x16_bf16 v[98:113], v[220:223], v[174:177], 0
	ds_read_b128 v[220:223], v238 offset:6688
	s_waitcnt lgkmcnt(2)
	v_mfma_f32_32x32x16_bf16 v[114:129], v[224:227], v[174:177], 0
	s_nop 7
	v_max3_f32 v251, v66, s63, v67
	v_max3_f32 v254, v68, s63, v69
	v_max3_f32 v251, v251, v70, v71
	v_max3_f32 v254, v254, v72, v73
	v_max3_f32 v251, v251, v74, v75
	v_max3_f32 v254, v254, v76, v77
	v_max3_f32 v251, v251, v78, v79
	v_max3_f32 v254, v254, v80, v81
	v_max3_f32 v251, v251, v82, v83
	v_max3_f32 v254, v254, v84, v85
	v_max3_f32 v251, v251, v86, v87
	v_max3_f32 v254, v254, v88, v89
	v_max3_f32 v251, v251, v90, v91
	ds_read_b128 v[224:227], v238 offset:64
	s_waitcnt lgkmcnt(2)
	v_mfma_f32_32x32x16_bf16 v[98:113], v[230:233], v[166:169], v[98:113]
	v_max3_f32 v254, v254, v92, v93
	v_max3_f32 v251, v251, v94, v95
	v_max3_f32 v254, v254, v96, v97
	v_max_f32_e32 v251, v251, v254
	v_mov_b32_e32 v254, v251
	s_nop 1
	v_permlane32_swap_b32_e32 v254, v251
	v_max_f32_e32 v251, v251, v254
	v_mul_f32_e32 v251, 0x3e16c740, v251
	v_max_f32_e32 v254, v246, v246
	v_max_f32_e32 v251, v254, v251
	v_sub_f32_e32 v236, v246, v251
	v_exp_f32_e32 v236, v236
	v_mov_b32_e32 v246, v251
	v_cmp_neq_f32_e32 vcc, 1.0, v236
	s_cbranch_vccz .Latt_noscale0
	v_pk_mul_f32 v[50:51], v[50:51], v[236:237] op_sel_hi:[1,0]
	v_pk_mul_f32 v[52:53], v[52:53], v[236:237] op_sel_hi:[1,0]
	v_pk_mul_f32 v[54:55], v[54:55], v[236:237] op_sel_hi:[1,0]
	v_pk_mul_f32 v[56:57], v[56:57], v[236:237] op_sel_hi:[1,0]
	v_pk_mul_f32 v[58:59], v[58:59], v[236:237] op_sel_hi:[1,0]
	v_pk_mul_f32 v[60:61], v[60:61], v[236:237] op_sel_hi:[1,0]
	v_pk_mul_f32 v[62:63], v[62:63], v[236:237] op_sel_hi:[1,0]
	v_pk_mul_f32 v[64:65], v[64:65], v[236:237] op_sel_hi:[1,0]
	v_pk_mul_f32 v[34:35], v[34:35], v[236:237] op_sel_hi:[1,0]
	v_pk_mul_f32 v[36:37], v[36:37], v[236:237] op_sel_hi:[1,0]
	v_pk_mul_f32 v[38:39], v[38:39], v[236:237] op_sel_hi:[1,0]
	v_pk_mul_f32 v[40:41], v[40:41], v[236:237] op_sel_hi:[1,0]
	v_pk_mul_f32 v[42:43], v[42:43], v[236:237] op_sel_hi:[1,0]
	v_pk_mul_f32 v[44:45], v[44:45], v[236:237] op_sel_hi:[1,0]
	v_pk_mul_f32 v[46:47], v[46:47], v[236:237] op_sel_hi:[1,0]
	v_pk_mul_f32 v[48:49], v[48:49], v[236:237] op_sel_hi:[1,0]
; #define MFMA32(a, b, c) __builtin_amdgcn_mfma_f32_32x32x16_bf16((a), (b), (c), 0, 0, 0)
; DI unsigned pack2(float lo, float hi) { f32x2 v; v.x = lo; v.y = hi; return __builtin_bit_cast(unsigned, __builtin_convertvector(v, hwbf2)); }
;     ...
;         for (int r = 0; r < 16; ++r) mx = fmaxf(mx, S[g][mt][r]);
;       mx = fmaxf(mx, __shfl_xor(mx, 32)) * scl;
;       const float mnew = fmaxf(mrun[g], mx);
;       const float alpha = __builtin_amdgcn_exp2f(mrun[g] - mnew);
;       mrun[g] = mnew;
;       float ps = 0.f;
; #pragma unroll
;       for (int mt = 0; mt < 2; ++mt)
; #pragma unroll
;         for (int r = 0; r < 16; ++r) { float e = __builtin_amdgcn_exp2f(fmaf(S[g][mt][r], scl, -mnew)); S[g][mt][r] = e; ps += e; }
;       lsum[g] = lsum[g] * alpha + ps;
;       if (__builtin_amdgcn_ballot_w64(alpha != 1.f) != 0ull) {
; #pragma unroll
;         for (int d = 0; d < 2; ++d)
; #pragma unroll
;           for (int r = 0; r < 16; ++r) O[g][d][r] *= alpha;
;       }
;     }
; #pragma unroll
;     for (int mt = 0; mt < 2; ++mt)
; #pragma unroll
;       for (int s2 = 0; s2 < 2; ++s2) {
;         bf16x8 pf[2];
; #pragma unroll
;         for (int g = 0; g < 2; ++g) {
;           unsigned pk[4];
; #pragma unroll
;           for (int q = 0; q < 4; ++q) pk[q] = pack2(S[g][mt][8 * s2 + 2 * q], S[g][mt][8 * s2 + 2 * q + 1]);
;           pf[g] = __builtin_bit_cast(bf16x8, (u32x4{pk[0], pk[1], pk[2], pk[3]}));
;         }
; #pragma unroll
;         for (int d = 0; d < 2; ++d) {
;           const u16* vp = Vs + (d * 32 + l31) * 68 + mt * 32 + s2 * 16 + 4 * hh;
;           u32x2 lo = *(const u32x2*)vp, hi = *(const u32x2*)(vp + 8);
;           const bf16x8 va = __builtin_bit_cast(bf16x8, (u32x4{lo.x, lo.y, hi.x, hi.y}));
;           O[0][d] = MFMA32(va, pf[0], O[0][d]);
;           O[1][d] = MFMA32(va, pf[1], O[1][d]);
;         }
;       }
.Latt_noscale0:
	v_fma_f32 v66, v66, s56, -v251
	v_fma_f32 v67, v67, s56, -v251
	ds_read_b128 v[230:233], v238 offset:6720
	s_waitcnt lgkmcnt(2)
	v_mfma_f32_32x32x16_bf16 v[114:129], v[220:223], v[166:169], v[114:129]
	v_exp_f32_e32 v66, v66
	v_exp_f32_e32 v67, v67
	v_fma_f32 v68, v68, s56, -v251
	v_add_f32_e32 v254, 0, v66
	v_fma_f32 v69, v69, s56, -v251
	v_add_f32_e32 v254, v67, v254
	v_exp_f32_e32 v68, v68
	v_exp_f32_e32 v69, v69
	v_fma_f32 v70, v70, s56, -v251
	v_add_f32_e32 v254, v68, v254
	v_fma_f32 v71, v71, s56, -v251
	v_add_f32_e32 v254, v69, v254
	v_exp_f32_e32 v70, v70
	v_exp_f32_e32 v71, v71
	ds_read_b128 v[220:223], v238 offset:96
	s_waitcnt lgkmcnt(2)
	v_mfma_f32_32x32x16_bf16 v[98:113], v[224:227], v[162:165], v[98:113]
	v_fma_f32 v72, v72, s56, -v251
	v_add_f32_e32 v254, v70, v254
	v_fma_f32 v73, v73, s56, -v251
	v_add_f32_e32 v254, v71, v254
	v_exp_f32_e32 v72, v72
	v_exp_f32_e32 v73, v73
	v_fma_f32 v74, v74, s56, -v251
	v_add_f32_e32 v254, v72, v254
	v_fma_f32 v75, v75, s56, -v251
	v_add_f32_e32 v254, v73, v254
	v_exp_f32_e32 v74, v74
	v_exp_f32_e32 v75, v75
	v_fma_f32 v76, v76, s56, -v251
	v_add_f32_e32 v254, v74, v254
	ds_read_b128 v[224:227], v238 offset:6752
	s_waitcnt lgkmcnt(2)
	v_mfma_f32_32x32x16_bf16 v[114:129], v[230:233], v[162:165], v[114:129]
	v_fma_f32 v77, v77, s56, -v251
	v_add_f32_e32 v254, v75, v254
	v_exp_f32_e32 v76, v76
	v_exp_f32_e32 v77, v77
	v_fma_f32 v78, v78, s56, -v251
	v_add_f32_e32 v254, v76, v254
	v_fma_f32 v79, v79, s56, -v251
	v_add_f32_e32 v254, v77, v254
	v_exp_f32_e32 v78, v78
	v_exp_f32_e32 v79, v79
	v_fma_f32 v80, v80, s56, -v251
	v_add_f32_e32 v254, v78, v254
	v_fma_f32 v81, v81, s56, -v251
	v_add_f32_e32 v254, v79, v254
	ds_read_b128 v[230:233], v238 offset:128
	s_waitcnt lgkmcnt(2)
	v_mfma_f32_32x32x16_bf16 v[98:113], v[220:223], v[150:153], v[98:113]
	v_exp_f32_e32 v80, v80
	v_exp_f32_e32 v81, v81
	v_fma_f32 v82, v82, s56, -v251
	v_add_f32_e32 v254, v80, v254
	v_fma_f32 v83, v83, s56, -v251
	v_add_f32_e32 v254, v81, v254
	v_exp_f32_e32 v82, v82
	v_exp_f32_e32 v83, v83
	v_fma_f32 v84, v84, s56, -v251
	v_add_f32_e32 v254, v82, v254
	v_fma_f32 v85, v85, s56, -v251
	v_add_f32_e32 v254, v83, v254
	v_exp_f32_e32 v84, v84
	v_exp_f32_e32 v85, v85
	ds_read_b128 v[220:223], v238 offset:6784
	s_waitcnt lgkmcnt(2)
	v_mfma_f32_32x32x16_bf16 v[114:129], v[224:227], v[150:153], v[114:129]
	v_fma_f32 v86, v86, s56, -v251
	v_add_f32_e32 v254, v84, v254
	v_fma_f32 v87, v87, s56, -v251
	v_add_f32_e32 v254, v85, v254
	v_exp_f32_e32 v86, v86
	v_exp_f32_e32 v87, v87
	v_fma_f32 v88, v88, s56, -v251
	v_add_f32_e32 v254, v86, v254
	v_fma_f32 v89, v89, s56, -v251
	v_add_f32_e32 v254, v87, v254
	v_exp_f32_e32 v88, v88
	v_exp_f32_e32 v89, v89
	v_fma_f32 v90, v90, s56, -v251
	v_add_f32_e32 v254, v88, v254
	ds_read_b128 v[224:227], v238 offset:160
	s_waitcnt lgkmcnt(2)
	v_mfma_f32_32x32x16_bf16 v[98:113], v[230:233], v[146:149], v[98:113]
	v_fma_f32 v91, v91, s56, -v251
	v_add_f32_e32 v254, v89, v254
	v_exp_f32_e32 v90, v90
	v_exp_f32_e32 v91, v91
	v_fma_f32 v92, v92, s56, -v251
	v_add_f32_e32 v254, v90, v254
	v_fma_f32 v93, v93, s56, -v251
	v_add_f32_e32 v254, v91, v254
	v_exp_f32_e32 v92, v92
	v_exp_f32_e32 v93, v93
	v_fma_f32 v94, v94, s56, -v251
	v_add_f32_e32 v254, v92, v254
	v_fma_f32 v95, v95, s56, -v251
	v_add_f32_e32 v254, v93, v254
	ds_read_b128 v[230:233], v238 offset:6816
	s_waitcnt lgkmcnt(2)
	v_mfma_f32_32x32x16_bf16 v[114:129], v[220:223], v[146:149], v[114:129]
	v_exp_f32_e32 v94, v94
	v_exp_f32_e32 v95, v95
	v_fma_f32 v96, v96, s56, -v251
	v_add_f32_e32 v254, v94, v254
	v_fma_f32 v97, v97, s56, -v251
	v_add_f32_e32 v254, v95, v254
	v_exp_f32_e32 v96, v96
	v_exp_f32_e32 v97, v97
	v_add_f32_e32 v254, v96, v254
	v_add_f32_e32 v254, v97, v254
	v_fmac_f32_e32 v254, v247, v236
	v_mov_b32_e32 v247, v254
	v_cvt_pk_bf16_f32 v66, v66, v67
	v_cvt_pk_bf16_f32 v67, v68, v69
	s_waitcnt lgkmcnt(1)
	v_mfma_f32_32x32x16_bf16 v[98:113], v[224:227], v[134:137], v[98:113]
	v_cvt_pk_bf16_f32 v68, v70, v71
	v_cvt_pk_bf16_f32 v69, v72, v73
	v_cvt_pk_bf16_f32 v70, v74, v75
	v_cvt_pk_bf16_f32 v71, v76, v77
	v_cvt_pk_bf16_f32 v72, v78, v79
	v_cvt_pk_bf16_f32 v73, v80, v81
	v_cvt_pk_bf16_f32 v74, v82, v83
	v_cvt_pk_bf16_f32 v75, v84, v85
	v_cvt_pk_bf16_f32 v76, v86, v87
	v_cvt_pk_bf16_f32 v77, v88, v89
	v_cvt_pk_bf16_f32 v78, v90, v91
	v_cvt_pk_bf16_f32 v79, v92, v93
	v_cvt_pk_bf16_f32 v80, v94, v95
	v_cvt_pk_bf16_f32 v81, v96, v97
	s_waitcnt lgkmcnt(0)
	v_mfma_f32_32x32x16_bf16 v[114:129], v[230:233], v[134:137], v[114:129]
	ds_read2_b64 v[220:223], v214 offset0:128 offset1:130
	ds_read2_b64 v[224:227], v216 offset0:128 offset1:130
	ds_read2_b64 v[230:233], v214 offset0:132 offset1:134
	s_waitcnt lgkmcnt(2)
	v_mfma_f32_32x32x16_bf16 v[50:65], v[220:223], v[66:69], v[50:65]
	s_nop 9
	v_max3_f32 v251, v98, s63, v99
	v_max3_f32 v254, v100, s63, v101
	v_max3_f32 v251, v251, v102, v103
	v_max3_f32 v254, v254, v104, v105
	v_max3_f32 v251, v251, v106, v107
	v_max3_f32 v254, v254, v108, v109
	v_max3_f32 v251, v251, v110, v111
	v_max3_f32 v254, v254, v112, v113
	v_max3_f32 v251, v251, v114, v115
	v_max3_f32 v254, v254, v116, v117
	v_max3_f32 v251, v251, v118, v119
	v_max3_f32 v254, v254, v120, v121
	v_max3_f32 v251, v251, v122, v123
	v_max3_f32 v254, v254, v124, v125
	v_max3_f32 v251, v251, v126, v127
	v_max3_f32 v254, v254, v128, v129
	v_max_f32_e32 v251, v251, v254
	v_mov_b32_e32 v254, v251
	s_nop 1
	v_permlane32_swap_b32_e32 v254, v251
	v_max_f32_e32 v251, v251, v254
	v_mul_f32_e32 v251, 0x3e16c740, v251
	v_max_f32_e32 v254, v249, v249
	ds_read2_b64 v[220:223], v216 offset0:132 offset1:134
	s_waitcnt lgkmcnt(2)
	v_mfma_f32_32x32x16_bf16 v[34:49], v[224:227], v[66:69], v[34:49]
	v_max_f32_e32 v251, v254, v251
	v_sub_f32_e32 v250, v249, v251
	v_exp_f32_e32 v250, v250
	v_mov_b32_e32 v249, v251
	v_cmp_neq_f32_e32 vcc, 1.0, v250
	s_cbranch_vccz .Latt_noscale1
	v_pk_mul_f32 v[18:19], v[18:19], v[250:251] op_sel_hi:[1,0]
	v_pk_mul_f32 v[20:21], v[20:21], v[250:251] op_sel_hi:[1,0]
	v_pk_mul_f32 v[22:23], v[22:23], v[250:251] op_sel_hi:[1,0]
	v_pk_mul_f32 v[24:25], v[24:25], v[250:251] op_sel_hi:[1,0]
	v_pk_mul_f32 v[26:27], v[26:27], v[250:251] op_sel_hi:[1,0]
	v_pk_mul_f32 v[28:29], v[28:29], v[250:251] op_sel_hi:[1,0]
	v_pk_mul_f32 v[30:31], v[30:31], v[250:251] op_sel_hi:[1,0]
	v_pk_mul_f32 v[32:33], v[32:33], v[250:251] op_sel_hi:[1,0]
	v_pk_mul_f32 v[2:3], v[2:3], v[250:251] op_sel_hi:[1,0]
	v_pk_mul_f32 v[4:5], v[4:5], v[250:251] op_sel_hi:[1,0]
	v_pk_mul_f32 v[6:7], v[6:7], v[250:251] op_sel_hi:[1,0]
	v_pk_mul_f32 v[8:9], v[8:9], v[250:251] op_sel_hi:[1,0]
	v_pk_mul_f32 v[10:11], v[10:11], v[250:251] op_sel_hi:[1,0]
	v_pk_mul_f32 v[12:13], v[12:13], v[250:251] op_sel_hi:[1,0]
	v_pk_mul_f32 v[14:15], v[14:15], v[250:251] op_sel_hi:[1,0]
	v_pk_mul_f32 v[16:17], v[16:17], v[250:251] op_sel_hi:[1,0]
; #define MFMA32(a, b, c) __builtin_amdgcn_mfma_f32_32x32x16_bf16((a), (b), (c), 0, 0, 0)
; DI unsigned pack2(float lo, float hi) { f32x2 v; v.x = lo; v.y = hi; return __builtin_bit_cast(unsigned, __builtin_convertvector(v, hwbf2)); }
;     ...
;       for (int mt = 0; mt < 2; ++mt)
; #pragma unroll
;         for (int r = 0; r < 16; ++r) { float e = __builtin_amdgcn_exp2f(fmaf(S[g][mt][r], scl, -mnew)); S[g][mt][r] = e; ps += e; }
;       lsum[g] = lsum[g] * alpha + ps;
;       if (__builtin_amdgcn_ballot_w64(alpha != 1.f) != 0ull) {
; #pragma unroll
;         for (int d = 0; d < 2; ++d)
; #pragma unroll
;           for (int r = 0; r < 16; ++r) O[g][d][r] *= alpha;
;       }
;     }
; #pragma unroll
;     for (int mt = 0; mt < 2; ++mt)
; #pragma unroll
;       for (int s2 = 0; s2 < 2; ++s2) {
;         bf16x8 pf[2];
; #pragma unroll
;         for (int g = 0; g < 2; ++g) {
;           unsigned pk[4];
; #pragma unroll
;           for (int q = 0; q < 4; ++q) pk[q] = pack2(S[g][mt][8 * s2 + 2 * q], S[g][mt][8 * s2 + 2 * q + 1]);
;           pf[g] = __builtin_bit_cast(bf16x8, (u32x4{pk[0], pk[1], pk[2], pk[3]}));
;         }
; #pragma unroll
;         for (int d = 0; d < 2; ++d) {
;           const u16* vp = Vs + (d * 32 + l31) * 68 + mt * 32 + s2 * 16 + 4 * hh;
;           u32x2 lo = *(const u32x2*)vp, hi = *(const u32x2*)(vp + 8);
;           const bf16x8 va = __builtin_bit_cast(bf16x8, (u32x4{lo.x, lo.y, hi.x, hi.y}));
;           O[0][d] = MFMA32(va, pf[0], O[0][d]);
;           O[1][d] = MFMA32(va, pf[1], O[1][d]);
;         }
;       }
.Latt_noscale1:
	v_fma_f32 v98, v98, s56, -v251
	v_fma_f32 v99, v99, s56, -v251
	v_exp_f32_e32 v98, v98
	v_exp_f32_e32 v99, v99
	v_fma_f32 v100, v100, s56, -v251
	v_add_f32_e32 v254, 0, v98
	v_fma_f32 v101, v101, s56, -v251
	v_add_f32_e32 v254, v99, v254
	v_exp_f32_e32 v100, v100
	v_exp_f32_e32 v101, v101
	v_fma_f32 v102, v102, s56, -v251
	v_add_f32_e32 v254, v100, v254
	v_fma_f32 v103, v103, s56, -v251
	v_add_f32_e32 v254, v101, v254
	v_exp_f32_e32 v102, v102
	v_exp_f32_e32 v103, v103
	ds_read2_b64 v[224:227], v214 offset0:136 offset1:138
	s_waitcnt lgkmcnt(2)
	v_mfma_f32_32x32x16_bf16 v[50:65], v[230:233], v[70:73], v[50:65]
	v_fma_f32 v104, v104, s56, -v251
	v_add_f32_e32 v254, v102, v254
	v_fma_f32 v105, v105, s56, -v251
	v_add_f32_e32 v254, v103, v254
	v_exp_f32_e32 v104, v104
	v_exp_f32_e32 v105, v105
	v_fma_f32 v106, v106, s56, -v251
	v_add_f32_e32 v254, v104, v254
	v_fma_f32 v107, v107, s56, -v251
	v_add_f32_e32 v254, v105, v254
	v_exp_f32_e32 v106, v106
	v_exp_f32_e32 v107, v107
	v_fma_f32 v108, v108, s56, -v251
	v_add_f32_e32 v254, v106, v254
	v_fma_f32 v109, v109, s56, -v251
	v_add_f32_e32 v254, v107, v254
	v_exp_f32_e32 v108, v108
	v_exp_f32_e32 v109, v109
	v_fma_f32 v110, v110, s56, -v251
	v_add_f32_e32 v254, v108, v254
	ds_read2_b64 v[230:233], v216 offset0:136 offset1:138
	s_waitcnt lgkmcnt(2)
	v_mfma_f32_32x32x16_bf16 v[34:49], v[220:223], v[70:73], v[34:49]
	v_fma_f32 v111, v111, s56, -v251
	v_add_f32_e32 v254, v109, v254
	v_exp_f32_e32 v110, v110
	v_exp_f32_e32 v111, v111
	v_fma_f32 v112, v112, s56, -v251
	v_add_f32_e32 v254, v110, v254
	v_fma_f32 v113, v113, s56, -v251
	v_add_f32_e32 v254, v111, v254
	v_exp_f32_e32 v112, v112
	v_exp_f32_e32 v113, v113
	v_fma_f32 v114, v114, s56, -v251
	v_add_f32_e32 v254, v112, v254
	v_fma_f32 v115, v115, s56, -v251
	v_add_f32_e32 v254, v113, v254
	v_exp_f32_e32 v114, v114
	v_exp_f32_e32 v115, v115
	v_fma_f32 v116, v116, s56, -v251
	v_add_f32_e32 v254, v114, v254
	v_fma_f32 v117, v117, s56, -v251
	v_add_f32_e32 v254, v115, v254
	v_exp_f32_e32 v116, v116
	ds_read2_b64 v[220:223], v214 offset0:140 offset1:142
	s_waitcnt lgkmcnt(2)
	v_mfma_f32_32x32x16_bf16 v[50:65], v[224:227], v[74:77], v[50:65]
	v_exp_f32_e32 v117, v117
	v_fma_f32 v118, v118, s56, -v251
	v_add_f32_e32 v254, v116, v254
	v_fma_f32 v119, v119, s56, -v251
	v_add_f32_e32 v254, v117, v254
	v_exp_f32_e32 v118, v118
	v_exp_f32_e32 v119, v119
	v_fma_f32 v120, v120, s56, -v251
	v_add_f32_e32 v254, v118, v254
	v_fma_f32 v121, v121, s56, -v251
	v_add_f32_e32 v254, v119, v254
	v_exp_f32_e32 v120, v120
	v_exp_f32_e32 v121, v121
	v_fma_f32 v122, v122, s56, -v251
	v_add_f32_e32 v254, v120, v254
	v_fma_f32 v123, v123, s56, -v251
	v_add_f32_e32 v254, v121, v254
	v_exp_f32_e32 v122, v122
	v_exp_f32_e32 v123, v123
	v_fma_f32 v124, v124, s56, -v251
	ds_read2_b64 v[224:227], v216 offset0:140 offset1:142
	s_waitcnt lgkmcnt(2)
	v_mfma_f32_32x32x16_bf16 v[34:49], v[230:233], v[74:77], v[34:49]
	v_add_f32_e32 v254, v122, v254
	v_fma_f32 v125, v125, s56, -v251
	v_add_f32_e32 v254, v123, v254
	v_exp_f32_e32 v124, v124
	v_exp_f32_e32 v125, v125
	v_fma_f32 v126, v126, s56, -v251
	v_add_f32_e32 v254, v124, v254
	v_fma_f32 v127, v127, s56, -v251
	v_add_f32_e32 v254, v125, v254
	v_exp_f32_e32 v126, v126
	v_exp_f32_e32 v127, v127
	v_fma_f32 v128, v128, s56, -v251
	v_add_f32_e32 v254, v126, v254
	v_fma_f32 v129, v129, s56, -v251
	v_add_f32_e32 v254, v127, v254
	v_exp_f32_e32 v128, v128
	v_exp_f32_e32 v129, v129
	v_add_f32_e32 v254, v128, v254
	v_add_f32_e32 v254, v129, v254
	v_fmac_f32_e32 v254, v248, v250
	v_mov_b32_e32 v248, v254
	s_waitcnt lgkmcnt(1)
	v_mfma_f32_32x32x16_bf16 v[50:65], v[220:223], v[78:81], v[50:65]
	v_cvt_pk_bf16_f32 v98, v98, v99
	v_cvt_pk_bf16_f32 v99, v100, v101
	v_cvt_pk_bf16_f32 v100, v102, v103
	v_cvt_pk_bf16_f32 v101, v104, v105
	v_cvt_pk_bf16_f32 v102, v106, v107
	v_cvt_pk_bf16_f32 v103, v108, v109
	v_cvt_pk_bf16_f32 v104, v110, v111
	v_cvt_pk_bf16_f32 v105, v112, v113
	v_cvt_pk_bf16_f32 v106, v114, v115
	v_cvt_pk_bf16_f32 v107, v116, v117
	v_cvt_pk_bf16_f32 v108, v118, v119
	v_cvt_pk_bf16_f32 v109, v120, v121
	v_cvt_pk_bf16_f32 v110, v122, v123
	v_cvt_pk_bf16_f32 v111, v124, v125
	v_cvt_pk_bf16_f32 v112, v126, v127
	v_cvt_pk_bf16_f32 v113, v128, v129
	v_lshl_add_u64 v[204:205], v[204:205], 0, s[50:51]
	v_lshl_add_u64 v[206:207], v[206:207], 0, s[50:51]
	v_lshl_add_u64 v[208:209], v[208:209], 0, s[64:65]
	v_lshl_add_u64 v[210:211], v[210:211], 0, s[64:65]
	v_lshl_add_u64 v[212:213], v[212:213], 0, s[64:65]
	s_waitcnt lgkmcnt(0)
	v_mfma_f32_32x32x16_bf16 v[34:49], v[224:227], v[78:81], v[34:49]
	ds_read2_b64 v[220:223], v214 offset0:128 offset1:130
	ds_read2_b64 v[224:227], v216 offset0:128 offset1:130
	ds_read2_b64 v[230:233], v214 offset0:132 offset1:134
	s_waitcnt lgkmcnt(2)
	v_mfma_f32_32x32x16_bf16 v[18:33], v[220:223], v[98:101], v[18:33]
	ds_read2_b64 v[220:223], v216 offset0:132 offset1:134
	s_waitcnt lgkmcnt(2)
	v_mfma_f32_32x32x16_bf16 v[2:17], v[224:227], v[98:101], v[2:17]
	ds_read2_b64 v[224:227], v214 offset0:136 offset1:138
	s_waitcnt lgkmcnt(2)
	v_mfma_f32_32x32x16_bf16 v[18:33], v[230:233], v[102:105], v[18:33]
	ds_read2_b64 v[230:233], v216 offset0:136 offset1:138
	s_waitcnt lgkmcnt(2)
	v_mfma_f32_32x32x16_bf16 v[2:17], v[220:223], v[102:105], v[2:17]
	ds_read2_b64 v[220:223], v214 offset0:140 offset1:142
	s_waitcnt lgkmcnt(2)
	v_mfma_f32_32x32x16_bf16 v[18:33], v[224:227], v[106:109], v[18:33]
	ds_read2_b64 v[224:227], v216 offset0:140 offset1:142
	s_waitcnt lgkmcnt(2)
	v_mfma_f32_32x32x16_bf16 v[2:17], v[230:233], v[106:109], v[2:17]
	s_waitcnt lgkmcnt(1)
	v_mfma_f32_32x32x16_bf16 v[18:33], v[220:223], v[110:113], v[18:33]
	s_waitcnt lgkmcnt(0)
	v_mfma_f32_32x32x16_bf16 v[2:17], v[224:227], v[110:113], v[2:17]
	s_add_i32 s2, s2, -1
	s_cmp_eq_u32 s2, 0
	s_cbranch_scc0 .Latt_kt
	v_mov_b32_e32 v232, 0x47
